# in-proj epilogue VALU trimmed: rope default moves skipped on non-rope waves, row-group store address strength-reduced, dead rstd address code removed
# speedup vs baseline: 1.0058x; 1.0058x over previous
;     __device__ __forceinline__ void operator()(const pg8::f32x4 (&acc)[2][2][4][2], const pg8::Unit& u, int wr, int wc, int fr, int fq) const {
;     ...
;                 const int row = row0 + ai * 128 + m * 16;
;                 const int tok = row & (SEQ - 1);
;                 bf16_t* rowp = base + (size_t)((row >> 13) * LP + PADF + NMETA + tok) * ldc + col0;
;                 const float scr = sc * rstd[row];
;                 f32x4 c0 = {1.f, 1.f, 1.f, 1.f}, c1 = c0, s0 = {0.f, 0.f, 0.f, 0.f}, s1 = s0;
;                 if (dorope) {
;                     const int pos = NMETA + tok;
;                     if (fq < 2) { c0 = *(const f32x4*)(ropec + pos * 8); c1 = *(const f32x4*)(ropec + pos * 8 + 4); s0 = *(const f32x4*)(ropes + pos * 8); s1 = *(const f32x4*)(ropes + pos * 8 + 4); }
;                 }
; #pragma unroll
;                 for (int bj = 0; bj < 2; ++bj) {
;                     f32x4 v0 = acc[ai][bj][m][0] * scr, v1 = acc[ai][bj][m][1] * scr;
;                     if (dorope) {
;                         f32x4 p0, p1;
; #pragma unroll
;                         for (int e = 0; e < 4; ++e) { p0[e] = __shfl_xor(v0[e], 16); p1[e] = __shfl_xor(v1[e], 16); }
;                         v0 = v0 * c0 + (p0 * s0) * sgn; v1 = v1 * c1 + (p1 * s1) * sgn;
;                     }
.LBB0_341:
	s_lshl_b32 s0, s0, 9
	s_add_u32 s0, s20, s0
	s_addc_u32 s1, s21, 0
	v_mov_b32_e32 v165, v0
	v_lshl_add_u64 v[168:169], s[0:1], 0, v[164:165]
	v_ashrrev_i32_e32 v126, 13, v166
	s_movk_i32 s0, 0x2080
	v_mad_i32_i24 v165, v126, s0, v221
	v_add_u32_e32 v126, v165, v167
	v_ashrrev_i32_e32 v127, 31, v126
	v_mul_lo_u32 v167, s2, v127
	v_mul_lo_u32 v175, s3, v126
	v_mad_u64_u32 v[126:127], s[0:1], s2, v126, 0
	v_mov_b32_e32 v171, v170
	v_add3_u32 v127, v127, v167, v175
	v_cvt_pk_bf16_f32 v130, v130, v131
	v_cvt_pk_bf16_f32 v131, v132, v133
	v_cvt_pk_bf16_f32 v133, v128, v129
	v_mov_b32_e32 v128, v170
	v_mov_b32_e32 v129, v170
	v_lshl_add_u64 v[126:127], v[126:127], 1, v[168:169]
	v_mov_b64_e32 v[232:233], v[126:127]
	v_cvt_pk_bf16_f32 v132, v172, v173
	v_pk_mul_f32 v[124:125], v[124:125], v[128:129]
	v_pk_mul_f32 v[122:123], v[122:123], v[170:171]
	v_pk_mul_f32 v[120:121], v[120:121], v[128:129]
	s_and_b64 vcc, exec, s[46:47]
	v_pk_mul_f32 v[118:119], v[118:119], v[170:171]
	global_store_dwordx4 v[126:127], v[130:133], off
	s_cbranch_vccnz .LBB0_343
	v_and_b32_e32 v129, 64, v218
	v_xor_b32_e32 v128, 16, v218
	v_add_u32_e32 v129, 64, v129
	v_cmp_lt_i32_e32 vcc, v128, v129
	s_nop 1
	v_cndmask_b32_e32 v128, v218, v128, vcc
	v_lshlrev_b32_e32 v167, 2, v128
	ds_bpermute_b32 v128, v167, v122
	ds_bpermute_b32 v129, v167, v123
	ds_bpermute_b32 v130, v167, v118
	ds_bpermute_b32 v132, v167, v124
	ds_bpermute_b32 v133, v167, v125
	ds_bpermute_b32 v131, v167, v119
	ds_bpermute_b32 v170, v167, v120
	ds_bpermute_b32 v171, v167, v121
	s_waitcnt lgkmcnt(6)
	v_pk_mul_f32 v[128:129], v[146:147], v[128:129]
	s_waitcnt lgkmcnt(3)
	v_pk_mul_f32 v[132:133], v[148:149], v[132:133]
	v_pk_mul_f32 v[128:129], v[156:157], v[128:129]
	s_waitcnt lgkmcnt(2)
	v_pk_mul_f32 v[130:131], v[142:143], v[130:131]
	v_pk_fma_f32 v[122:123], v[122:123], v[138:139], v[128:129]
	s_waitcnt lgkmcnt(0)
	v_pk_mul_f32 v[128:129], v[144:145], v[170:171]
	v_pk_mul_f32 v[132:133], v[158:159], v[132:133]
	v_pk_mul_f32 v[130:131], v[156:157], v[130:131]
	v_pk_mul_f32 v[128:129], v[158:159], v[128:129]
	v_pk_fma_f32 v[124:125], v[124:125], v[140:141], v[132:133]
	v_pk_fma_f32 v[120:121], v[120:121], v[136:137], v[128:129]
	v_pk_fma_f32 v[118:119], v[118:119], v[134:135], v[130:131]

;     __device__ __forceinline__ void operator()(const pg8::f32x4 (&acc)[2][2][4][2], const pg8::Unit& u, int wr, int wc, int fr, int fq) const {
;     ...
;                 const float scr = sc * rstd[row];
;                 f32x4 c0 = {1.f, 1.f, 1.f, 1.f}, c1 = c0, s0 = {0.f, 0.f, 0.f, 0.f}, s1 = s0;
;                 if (dorope) {
;                     const int pos = NMETA + tok;
;                     if (fq < 2) { c0 = *(const f32x4*)(ropec + pos * 8); c1 = *(const f32x4*)(ropec + pos * 8 + 4); s0 = *(const f32x4*)(ropes + pos * 8); s1 = *(const f32x4*)(ropes + pos * 8 + 4); }
;                 }
.LBB0_345:
	v_cvt_pk_bf16_f32 v122, v122, v123
	v_cvt_pk_bf16_f32 v123, v124, v125
	v_cvt_pk_bf16_f32 v124, v118, v119
	v_cvt_pk_bf16_f32 v125, v120, v121
	global_store_dwordx4 v[126:127], v[122:125], off offset:256
	v_mov_b32_e32 v134, v224
	s_movk_i32 s0, 0x1fdf
	v_bitop3_b32 v138, v166, s0, 16 bitop3:0xc8
	s_and_b64 vcc, exec, s[46:47]
	s_cbranch_vccnz .Lepi_nd2
	v_mov_b32_e32 v130, 0
	v_mov_b32_e32 v122, 1.0
	v_mov_b32_e32 v123, 1.0
	v_mov_b32_e32 v124, 1.0
	v_mov_b32_e32 v125, 1.0
	v_mov_b32_e32 v118, 1.0
	v_mov_b32_e32 v119, 1.0
	v_mov_b32_e32 v120, 1.0
	v_mov_b32_e32 v121, 1.0
	v_mov_b32_e32 v131, 0
	v_mov_b32_e32 v132, 0
	v_mov_b32_e32 v133, 0
	v_mov_b32_e32 v126, 0
	v_mov_b32_e32 v127, 0
	v_mov_b32_e32 v128, 0
	v_mov_b32_e32 v129, 0
.Lepi_nd2:
	s_and_saveexec_b64 s[20:21], s[30:31]
	s_cbranch_execz .LBB0_347
	v_readlane_b32 s0, v253, 20
	v_lshl_add_u32 v126, v138, 5, v220
	v_readlane_b32 s1, v253, 21
	s_nop 4
	global_load_dwordx4 v[122:125], v126, s[0:1]
	global_load_dwordx4 v[118:121], v126, s[0:1] offset:16
	v_readlane_b32 s0, v253, 22
	v_readlane_b32 s1, v253, 23
	s_nop 4
	global_load_dwordx4 v[130:133], v126, s[0:1]
	s_nop 0
	global_load_dwordx4 v[126:129], v126, s[0:1] offset:16
	s_waitcnt vmcnt(0)

;     __device__ __forceinline__ void operator()(const pg8::f32x4 (&acc)[2][2][4][2], const pg8::Unit& u, int wr, int wc, int fr, int fq) const {
;     ...
;                 const int row = row0 + ai * 128 + m * 16;
;                 const int tok = row & (SEQ - 1);
;                 bf16_t* rowp = base + (size_t)((row >> 13) * LP + PADF + NMETA + tok) * ldc + col0;
;                 const float scr = sc * rstd[row];
;                 f32x4 c0 = {1.f, 1.f, 1.f, 1.f}, c1 = c0, s0 = {0.f, 0.f, 0.f, 0.f}, s1 = s0;
;                 if (dorope) {
;                     const int pos = NMETA + tok;
;                     if (fq < 2) { c0 = *(const f32x4*)(ropec + pos * 8); c1 = *(const f32x4*)(ropec + pos * 8 + 4); s0 = *(const f32x4*)(ropes + pos * 8); s1 = *(const f32x4*)(ropes + pos * 8 + 4); }
;                 }
; #pragma unroll
;                 for (int bj = 0; bj < 2; ++bj) {
;                     f32x4 v0 = acc[ai][bj][m][0] * scr, v1 = acc[ai][bj][m][1] * scr;
.LBB0_351:
	v_mov_b32_e32 v135, v134
	v_cvt_pk_bf16_f32 v114, v114, v115
	v_cvt_pk_bf16_f32 v115, v116, v117
	v_cvt_pk_bf16_f32 v117, v112, v113
	v_mov_b32_e32 v112, v134
	v_mov_b32_e32 v113, v134
	s_mul_i32 s0, s2, 32
	s_mov_b32 s1, 0
	v_lshl_add_u64 v[110:111], v[232:233], 0, s[0:1]
	v_cvt_pk_bf16_f32 v116, v136, v137
	v_pk_mul_f32 v[108:109], v[108:109], v[112:113]
	v_pk_mul_f32 v[106:107], v[106:107], v[134:135]
	v_pk_mul_f32 v[104:105], v[104:105], v[112:113]
	s_and_b64 vcc, exec, s[46:47]
	v_pk_mul_f32 v[102:103], v[102:103], v[134:135]
	global_store_dwordx4 v[110:111], v[114:117], off
	s_cbranch_vccnz .LBB0_353
	v_and_b32_e32 v113, 64, v218
	v_xor_b32_e32 v112, 16, v218
	v_add_u32_e32 v113, 64, v113
	v_cmp_lt_i32_e32 vcc, v112, v113
	s_nop 1
	v_cndmask_b32_e32 v112, v218, v112, vcc
	v_lshlrev_b32_e32 v135, 2, v112
	ds_bpermute_b32 v112, v135, v106
	ds_bpermute_b32 v113, v135, v107
	ds_bpermute_b32 v114, v135, v102
	ds_bpermute_b32 v116, v135, v108
	ds_bpermute_b32 v117, v135, v109
	ds_bpermute_b32 v115, v135, v103
	ds_bpermute_b32 v134, v135, v104
	ds_bpermute_b32 v135, v135, v105
	s_waitcnt lgkmcnt(6)
	v_pk_mul_f32 v[112:113], v[130:131], v[112:113]
	s_waitcnt lgkmcnt(3)
	v_pk_mul_f32 v[116:117], v[132:133], v[116:117]
	v_pk_mul_f32 v[112:113], v[156:157], v[112:113]
	s_waitcnt lgkmcnt(2)
	v_pk_mul_f32 v[114:115], v[126:127], v[114:115]
	v_pk_fma_f32 v[106:107], v[106:107], v[122:123], v[112:113]
	s_waitcnt lgkmcnt(0)
	v_pk_mul_f32 v[112:113], v[128:129], v[134:135]
	v_pk_mul_f32 v[116:117], v[158:159], v[116:117]
	v_pk_mul_f32 v[114:115], v[156:157], v[114:115]
	v_pk_mul_f32 v[112:113], v[158:159], v[112:113]
	v_pk_fma_f32 v[108:109], v[108:109], v[124:125], v[116:117]
	v_pk_fma_f32 v[104:105], v[104:105], v[120:121], v[112:113]
	v_pk_fma_f32 v[102:103], v[102:103], v[118:119], v[114:115]

;     __device__ __forceinline__ void operator()(const pg8::f32x4 (&acc)[2][2][4][2], const pg8::Unit& u, int wr, int wc, int fr, int fq) const {
;     ...
;                 const float scr = sc * rstd[row];
;                 f32x4 c0 = {1.f, 1.f, 1.f, 1.f}, c1 = c0, s0 = {0.f, 0.f, 0.f, 0.f}, s1 = s0;
;                 if (dorope) {
;                     const int pos = NMETA + tok;
;                     if (fq < 2) { c0 = *(const f32x4*)(ropec + pos * 8); c1 = *(const f32x4*)(ropec + pos * 8 + 4); s0 = *(const f32x4*)(ropes + pos * 8); s1 = *(const f32x4*)(ropes + pos * 8 + 4); }
;                 }
.LBB0_355:
	v_cvt_pk_bf16_f32 v106, v106, v107
	v_cvt_pk_bf16_f32 v107, v108, v109
	v_cvt_pk_bf16_f32 v108, v102, v103
	v_cvt_pk_bf16_f32 v109, v104, v105
	global_store_dwordx4 v[110:111], v[106:109], off offset:256
	v_mov_b32_e32 v118, v225
	s_movk_i32 s0, 0x1fef
	v_bitop3_b32 v122, v166, s0, 32 bitop3:0xc8
	s_and_b64 vcc, exec, s[46:47]
	s_cbranch_vccnz .Lepi_nd3
	v_mov_b32_e32 v114, 0
	v_mov_b32_e32 v106, 1.0
	v_mov_b32_e32 v107, 1.0
	v_mov_b32_e32 v108, 1.0
	v_mov_b32_e32 v109, 1.0
	v_mov_b32_e32 v102, 1.0
	v_mov_b32_e32 v103, 1.0
	v_mov_b32_e32 v104, 1.0
	v_mov_b32_e32 v105, 1.0
	v_mov_b32_e32 v115, 0
	v_mov_b32_e32 v116, 0
	v_mov_b32_e32 v117, 0
	v_mov_b32_e32 v110, 0
	v_mov_b32_e32 v111, 0
	v_mov_b32_e32 v112, 0
	v_mov_b32_e32 v113, 0
.Lepi_nd3:
	s_and_saveexec_b64 s[20:21], s[30:31]
	s_cbranch_execz .LBB0_357
	v_readlane_b32 s0, v253, 20
	v_lshl_or_b32 v110, v122, 5, v220
	v_readlane_b32 s1, v253, 21
	s_nop 4
	global_load_dwordx4 v[106:109], v110, s[0:1]
	global_load_dwordx4 v[102:105], v110, s[0:1] offset:16
	v_readlane_b32 s0, v253, 22
	v_readlane_b32 s1, v253, 23
	s_nop 4
	global_load_dwordx4 v[114:117], v110, s[0:1]
	s_nop 0
	global_load_dwordx4 v[110:113], v110, s[0:1] offset:16
	s_waitcnt vmcnt(0)

;     __device__ __forceinline__ void operator()(const pg8::f32x4 (&acc)[2][2][4][2], const pg8::Unit& u, int wr, int wc, int fr, int fq) const {
;     ...
;                 const int row = row0 + ai * 128 + m * 16;
;                 const int tok = row & (SEQ - 1);
;                 bf16_t* rowp = base + (size_t)((row >> 13) * LP + PADF + NMETA + tok) * ldc + col0;
;                 const float scr = sc * rstd[row];
;                 f32x4 c0 = {1.f, 1.f, 1.f, 1.f}, c1 = c0, s0 = {0.f, 0.f, 0.f, 0.f}, s1 = s0;
;                 if (dorope) {
;                     const int pos = NMETA + tok;
;                     if (fq < 2) { c0 = *(const f32x4*)(ropec + pos * 8); c1 = *(const f32x4*)(ropec + pos * 8 + 4); s0 = *(const f32x4*)(ropes + pos * 8); s1 = *(const f32x4*)(ropes + pos * 8 + 4); }
;                 }
; #pragma unroll
;                 for (int bj = 0; bj < 2; ++bj) {
;                     f32x4 v0 = acc[ai][bj][m][0] * scr, v1 = acc[ai][bj][m][1] * scr;
.LBB0_361:
	v_mov_b32_e32 v119, v118
	v_cvt_pk_bf16_f32 v98, v98, v99
	v_cvt_pk_bf16_f32 v99, v100, v101
	v_cvt_pk_bf16_f32 v101, v96, v97
	v_mov_b32_e32 v96, v118
	v_mov_b32_e32 v97, v118
	s_mul_i32 s0, s2, 64
	s_mov_b32 s1, 0
	v_lshl_add_u64 v[94:95], v[232:233], 0, s[0:1]
	v_cvt_pk_bf16_f32 v100, v120, v121
	v_pk_mul_f32 v[92:93], v[92:93], v[96:97]
	v_pk_mul_f32 v[90:91], v[90:91], v[118:119]
	v_pk_mul_f32 v[88:89], v[88:89], v[96:97]
	s_and_b64 vcc, exec, s[46:47]
	v_pk_mul_f32 v[86:87], v[86:87], v[118:119]
	global_store_dwordx4 v[94:95], v[98:101], off
	s_cbranch_vccnz .LBB0_363
	v_and_b32_e32 v97, 64, v218
	v_xor_b32_e32 v96, 16, v218
	v_add_u32_e32 v97, 64, v97
	v_cmp_lt_i32_e32 vcc, v96, v97
	s_nop 1
	v_cndmask_b32_e32 v96, v218, v96, vcc
	v_lshlrev_b32_e32 v119, 2, v96
	ds_bpermute_b32 v96, v119, v90
	ds_bpermute_b32 v97, v119, v91
	ds_bpermute_b32 v98, v119, v86
	ds_bpermute_b32 v100, v119, v92
	ds_bpermute_b32 v101, v119, v93
	ds_bpermute_b32 v99, v119, v87
	ds_bpermute_b32 v118, v119, v88
	ds_bpermute_b32 v119, v119, v89
	s_waitcnt lgkmcnt(6)
	v_pk_mul_f32 v[96:97], v[114:115], v[96:97]
	s_waitcnt lgkmcnt(3)
	v_pk_mul_f32 v[100:101], v[116:117], v[100:101]
	v_pk_mul_f32 v[96:97], v[156:157], v[96:97]
	s_waitcnt lgkmcnt(2)
	v_pk_mul_f32 v[98:99], v[110:111], v[98:99]
	v_pk_fma_f32 v[90:91], v[90:91], v[106:107], v[96:97]
	s_waitcnt lgkmcnt(0)
	v_pk_mul_f32 v[96:97], v[112:113], v[118:119]
	v_pk_mul_f32 v[100:101], v[158:159], v[100:101]
	v_pk_mul_f32 v[98:99], v[156:157], v[98:99]
	v_pk_mul_f32 v[96:97], v[158:159], v[96:97]
	v_pk_fma_f32 v[92:93], v[92:93], v[108:109], v[100:101]
	v_pk_fma_f32 v[88:89], v[88:89], v[104:105], v[96:97]
	v_pk_fma_f32 v[86:87], v[86:87], v[102:103], v[98:99]

;     __device__ __forceinline__ void operator()(const pg8::f32x4 (&acc)[2][2][4][2], const pg8::Unit& u, int wr, int wc, int fr, int fq) const {
;     ...
;                 const float scr = sc * rstd[row];
;                 f32x4 c0 = {1.f, 1.f, 1.f, 1.f}, c1 = c0, s0 = {0.f, 0.f, 0.f, 0.f}, s1 = s0;
;                 if (dorope) {
;                     const int pos = NMETA + tok;
;                     if (fq < 2) { c0 = *(const f32x4*)(ropec + pos * 8); c1 = *(const f32x4*)(ropec + pos * 8 + 4); s0 = *(const f32x4*)(ropes + pos * 8); s1 = *(const f32x4*)(ropes + pos * 8 + 4); }
;                 }
.LBB0_365:
	v_cvt_pk_bf16_f32 v90, v90, v91
	v_cvt_pk_bf16_f32 v91, v92, v93
	v_cvt_pk_bf16_f32 v92, v86, v87
	v_cvt_pk_bf16_f32 v93, v88, v89
	global_store_dwordx4 v[94:95], v[90:93], off offset:256
	v_mov_b32_e32 v102, v226
	s_movk_i32 s0, 0x1fff
	v_bitop3_b32 v106, v166, s0, 48 bitop3:0xc8
	s_and_b64 vcc, exec, s[46:47]
	s_cbranch_vccnz .Lepi_nd4
	v_mov_b32_e32 v98, 0
	v_mov_b32_e32 v90, 1.0
	v_mov_b32_e32 v91, 1.0
	v_mov_b32_e32 v92, 1.0
	v_mov_b32_e32 v93, 1.0
	v_mov_b32_e32 v86, 1.0
	v_mov_b32_e32 v87, 1.0
	v_mov_b32_e32 v88, 1.0
	v_mov_b32_e32 v89, 1.0
	v_mov_b32_e32 v99, 0
	v_mov_b32_e32 v100, 0
	v_mov_b32_e32 v101, 0
	v_mov_b32_e32 v94, 0
	v_mov_b32_e32 v95, 0
	v_mov_b32_e32 v96, 0
	v_mov_b32_e32 v97, 0
.Lepi_nd4:
	s_and_saveexec_b64 s[20:21], s[30:31]
	s_cbranch_execz .LBB0_367
	v_readlane_b32 s0, v253, 20
	v_lshl_add_u32 v94, v106, 5, v220
	v_readlane_b32 s1, v253, 21
	s_nop 4
	global_load_dwordx4 v[90:93], v94, s[0:1]
	global_load_dwordx4 v[86:89], v94, s[0:1] offset:16
	v_readlane_b32 s0, v253, 22
	v_readlane_b32 s1, v253, 23
	s_nop 4
	global_load_dwordx4 v[98:101], v94, s[0:1]
	s_nop 0
	global_load_dwordx4 v[94:97], v94, s[0:1] offset:16
	s_waitcnt vmcnt(0)

;     __device__ __forceinline__ void operator()(const pg8::f32x4 (&acc)[2][2][4][2], const pg8::Unit& u, int wr, int wc, int fr, int fq) const {
;     ...
;                 const int row = row0 + ai * 128 + m * 16;
;                 const int tok = row & (SEQ - 1);
;                 bf16_t* rowp = base + (size_t)((row >> 13) * LP + PADF + NMETA + tok) * ldc + col0;
;                 const float scr = sc * rstd[row];
;                 f32x4 c0 = {1.f, 1.f, 1.f, 1.f}, c1 = c0, s0 = {0.f, 0.f, 0.f, 0.f}, s1 = s0;
;                 if (dorope) {
;                     const int pos = NMETA + tok;
;                     if (fq < 2) { c0 = *(const f32x4*)(ropec + pos * 8); c1 = *(const f32x4*)(ropec + pos * 8 + 4); s0 = *(const f32x4*)(ropes + pos * 8); s1 = *(const f32x4*)(ropes + pos * 8 + 4); }
;                 }
; #pragma unroll
;                 for (int bj = 0; bj < 2; ++bj) {
;                     f32x4 v0 = acc[ai][bj][m][0] * scr, v1 = acc[ai][bj][m][1] * scr;
.LBB0_371:
	v_mov_b32_e32 v103, v102
	v_cvt_pk_bf16_f32 v82, v82, v83
	v_cvt_pk_bf16_f32 v83, v84, v85
	v_cvt_pk_bf16_f32 v85, v80, v81
	v_mov_b32_e32 v80, v102
	v_mov_b32_e32 v81, v102
	s_mul_i32 s0, s2, 96
	s_mov_b32 s1, 0
	v_lshl_add_u64 v[78:79], v[232:233], 0, s[0:1]
	v_cvt_pk_bf16_f32 v84, v104, v105
	v_pk_mul_f32 v[76:77], v[76:77], v[80:81]
	v_pk_mul_f32 v[74:75], v[74:75], v[102:103]
	v_pk_mul_f32 v[72:73], v[72:73], v[80:81]
	s_and_b64 vcc, exec, s[46:47]
	v_pk_mul_f32 v[70:71], v[70:71], v[102:103]
	global_store_dwordx4 v[78:79], v[82:85], off
	s_cbranch_vccnz .LBB0_373
	v_and_b32_e32 v81, 64, v218
	v_xor_b32_e32 v80, 16, v218
	v_add_u32_e32 v81, 64, v81
	v_cmp_lt_i32_e32 vcc, v80, v81
	s_nop 1
	v_cndmask_b32_e32 v80, v218, v80, vcc
	v_lshlrev_b32_e32 v103, 2, v80
	ds_bpermute_b32 v80, v103, v74
	ds_bpermute_b32 v81, v103, v75
	ds_bpermute_b32 v82, v103, v70
	ds_bpermute_b32 v84, v103, v76
	ds_bpermute_b32 v85, v103, v77
	ds_bpermute_b32 v83, v103, v71
	ds_bpermute_b32 v102, v103, v72
	ds_bpermute_b32 v103, v103, v73
	s_waitcnt lgkmcnt(6)
	v_pk_mul_f32 v[80:81], v[98:99], v[80:81]
	s_waitcnt lgkmcnt(3)
	v_pk_mul_f32 v[84:85], v[100:101], v[84:85]
	v_pk_mul_f32 v[80:81], v[156:157], v[80:81]
	s_waitcnt lgkmcnt(2)
	v_pk_mul_f32 v[82:83], v[94:95], v[82:83]
	v_pk_fma_f32 v[74:75], v[74:75], v[90:91], v[80:81]
	s_waitcnt lgkmcnt(0)
	v_pk_mul_f32 v[80:81], v[96:97], v[102:103]
	v_pk_mul_f32 v[84:85], v[158:159], v[84:85]
	v_pk_mul_f32 v[82:83], v[156:157], v[82:83]
	v_pk_mul_f32 v[80:81], v[158:159], v[80:81]
	v_pk_fma_f32 v[76:77], v[76:77], v[92:93], v[84:85]
	v_pk_fma_f32 v[72:73], v[72:73], v[88:89], v[80:81]
	v_pk_fma_f32 v[70:71], v[70:71], v[86:87], v[82:83]

;     __device__ __forceinline__ void operator()(const pg8::f32x4 (&acc)[2][2][4][2], const pg8::Unit& u, int wr, int wc, int fr, int fq) const {
;     ...
;                 const float scr = sc * rstd[row];
;                 f32x4 c0 = {1.f, 1.f, 1.f, 1.f}, c1 = c0, s0 = {0.f, 0.f, 0.f, 0.f}, s1 = s0;
;                 if (dorope) {
;                     const int pos = NMETA + tok;
;                     if (fq < 2) { c0 = *(const f32x4*)(ropec + pos * 8); c1 = *(const f32x4*)(ropec + pos * 8 + 4); s0 = *(const f32x4*)(ropes + pos * 8); s1 = *(const f32x4*)(ropes + pos * 8 + 4); }
;                 }
.LBB0_375:
	v_add_u32_e32 v86, 0x80, v166
	v_cvt_pk_bf16_f32 v74, v74, v75
	v_cvt_pk_bf16_f32 v75, v76, v77
	v_cvt_pk_bf16_f32 v76, v70, v71
	v_cvt_pk_bf16_f32 v77, v72, v73
	global_store_dwordx4 v[78:79], v[74:77], off offset:256
	v_mov_b32_e32 v88, v227
	v_and_b32_e32 v87, 0x1fcf, v86
	s_and_b64 vcc, exec, s[46:47]
	s_cbranch_vccnz .Lepi_nd5
	v_mov_b32_e32 v82, 0
	v_mov_b32_e32 v74, 1.0
	v_mov_b32_e32 v75, 1.0
	v_mov_b32_e32 v76, 1.0
	v_mov_b32_e32 v77, 1.0
	v_mov_b32_e32 v70, 1.0
	v_mov_b32_e32 v71, 1.0
	v_mov_b32_e32 v72, 1.0
	v_mov_b32_e32 v73, 1.0
	v_mov_b32_e32 v83, 0
	v_mov_b32_e32 v84, 0
	v_mov_b32_e32 v85, 0
	v_mov_b32_e32 v78, 0
	v_mov_b32_e32 v79, 0
	v_mov_b32_e32 v80, 0
	v_mov_b32_e32 v81, 0
.Lepi_nd5:
	s_and_saveexec_b64 s[20:21], s[30:31]
	s_cbranch_execz .LBB0_377
	v_readlane_b32 s0, v253, 20
	v_lshl_or_b32 v78, v87, 5, v220
	v_readlane_b32 s1, v253, 21
	s_nop 4
	global_load_dwordx4 v[74:77], v78, s[0:1]
	global_load_dwordx4 v[70:73], v78, s[0:1] offset:16
	v_readlane_b32 s0, v253, 22
	v_readlane_b32 s1, v253, 23
	s_nop 4
	global_load_dwordx4 v[82:85], v78, s[0:1]
	s_nop 0
	global_load_dwordx4 v[78:81], v78, s[0:1] offset:16
	s_waitcnt vmcnt(0)

;     __device__ __forceinline__ void operator()(const pg8::f32x4 (&acc)[2][2][4][2], const pg8::Unit& u, int wr, int wc, int fr, int fq) const {
;     ...
;                 const int row = row0 + ai * 128 + m * 16;
;                 const int tok = row & (SEQ - 1);
;                 bf16_t* rowp = base + (size_t)((row >> 13) * LP + PADF + NMETA + tok) * ldc + col0;
;                 const float scr = sc * rstd[row];
;                 f32x4 c0 = {1.f, 1.f, 1.f, 1.f}, c1 = c0, s0 = {0.f, 0.f, 0.f, 0.f}, s1 = s0;
;                 if (dorope) {
;                     const int pos = NMETA + tok;
;                     if (fq < 2) { c0 = *(const f32x4*)(ropec + pos * 8); c1 = *(const f32x4*)(ropec + pos * 8 + 4); s0 = *(const f32x4*)(ropes + pos * 8); s1 = *(const f32x4*)(ropes + pos * 8 + 4); }
;                 }
; #pragma unroll
;                 for (int bj = 0; bj < 2; ++bj) {
;                     f32x4 v0 = acc[ai][bj][m][0] * scr, v1 = acc[ai][bj][m][1] * scr;
.LBB0_381:
	v_mov_b32_e32 v89, v88
	v_cvt_pk_bf16_f32 v66, v66, v67
	v_cvt_pk_bf16_f32 v67, v68, v69
	v_cvt_pk_bf16_f32 v69, v64, v65
	v_mov_b32_e32 v64, v88
	v_mov_b32_e32 v65, v88
	s_mul_i32 s0, s2, 256
	s_mov_b32 s1, 0
	v_lshl_add_u64 v[62:63], v[232:233], 0, s[0:1]
	v_cvt_pk_bf16_f32 v68, v90, v91
	v_pk_mul_f32 v[60:61], v[60:61], v[64:65]
	v_pk_mul_f32 v[58:59], v[58:59], v[88:89]
	v_pk_mul_f32 v[56:57], v[56:57], v[64:65]
	s_and_b64 vcc, exec, s[46:47]
	v_pk_mul_f32 v[54:55], v[54:55], v[88:89]
	global_store_dwordx4 v[62:63], v[66:69], off
	s_cbranch_vccnz .LBB0_383
	v_and_b32_e32 v65, 64, v218
	v_xor_b32_e32 v64, 16, v218
	v_add_u32_e32 v65, 64, v65
	v_cmp_lt_i32_e32 vcc, v64, v65
	s_nop 1
	v_cndmask_b32_e32 v64, v218, v64, vcc
	v_lshlrev_b32_e32 v87, 2, v64
	ds_bpermute_b32 v64, v87, v58
	ds_bpermute_b32 v65, v87, v59
	ds_bpermute_b32 v66, v87, v54
	ds_bpermute_b32 v68, v87, v60
	ds_bpermute_b32 v69, v87, v61
	ds_bpermute_b32 v67, v87, v55
	ds_bpermute_b32 v88, v87, v56
	ds_bpermute_b32 v89, v87, v57
	s_waitcnt lgkmcnt(6)
	v_pk_mul_f32 v[64:65], v[82:83], v[64:65]
	s_waitcnt lgkmcnt(3)
	v_pk_mul_f32 v[68:69], v[84:85], v[68:69]
	v_pk_mul_f32 v[64:65], v[156:157], v[64:65]
	s_waitcnt lgkmcnt(2)
	v_pk_mul_f32 v[66:67], v[78:79], v[66:67]
	v_pk_fma_f32 v[58:59], v[58:59], v[74:75], v[64:65]
	s_waitcnt lgkmcnt(0)
	v_pk_mul_f32 v[64:65], v[80:81], v[88:89]
	v_pk_mul_f32 v[68:69], v[158:159], v[68:69]
	v_pk_mul_f32 v[66:67], v[156:157], v[66:67]
	v_pk_mul_f32 v[64:65], v[158:159], v[64:65]
	v_pk_fma_f32 v[60:61], v[60:61], v[76:77], v[68:69]
	v_pk_fma_f32 v[56:57], v[56:57], v[72:73], v[64:65]
	v_pk_fma_f32 v[54:55], v[54:55], v[70:71], v[66:67]

;     __device__ __forceinline__ void operator()(const pg8::f32x4 (&acc)[2][2][4][2], const pg8::Unit& u, int wr, int wc, int fr, int fq) const {
;     ...
;                 const float scr = sc * rstd[row];
;                 f32x4 c0 = {1.f, 1.f, 1.f, 1.f}, c1 = c0, s0 = {0.f, 0.f, 0.f, 0.f}, s1 = s0;
;                 if (dorope) {
;                     const int pos = NMETA + tok;
;                     if (fq < 2) { c0 = *(const f32x4*)(ropec + pos * 8); c1 = *(const f32x4*)(ropec + pos * 8 + 4); s0 = *(const f32x4*)(ropes + pos * 8); s1 = *(const f32x4*)(ropes + pos * 8 + 4); }
;                 }
.LBB0_385:
	v_cvt_pk_bf16_f32 v58, v58, v59
	v_cvt_pk_bf16_f32 v59, v60, v61
	v_cvt_pk_bf16_f32 v60, v54, v55
	v_add_u32_e32 v54, 0x90, v166
	v_cvt_pk_bf16_f32 v61, v56, v57
	global_store_dwordx4 v[62:63], v[58:61], off offset:256
	v_mov_b32_e32 v70, v228
	v_and_b32_e32 v74, 0x1fdf, v54
	s_and_b64 vcc, exec, s[46:47]
	s_cbranch_vccnz .Lepi_nd6
	v_mov_b32_e32 v66, 0
	v_mov_b32_e32 v58, 1.0
	v_mov_b32_e32 v59, 1.0
	v_mov_b32_e32 v60, 1.0
	v_mov_b32_e32 v61, 1.0
	v_mov_b32_e32 v54, 1.0
	v_mov_b32_e32 v55, 1.0
	v_mov_b32_e32 v56, 1.0
	v_mov_b32_e32 v57, 1.0
	v_mov_b32_e32 v67, 0
	v_mov_b32_e32 v68, 0
	v_mov_b32_e32 v69, 0
	v_mov_b32_e32 v62, 0
	v_mov_b32_e32 v63, 0
	v_mov_b32_e32 v64, 0
	v_mov_b32_e32 v65, 0
.Lepi_nd6:
	s_and_saveexec_b64 s[20:21], s[30:31]
	s_cbranch_execz .LBB0_387
	v_readlane_b32 s0, v253, 20
	v_lshl_add_u32 v62, v74, 5, v220
	v_readlane_b32 s1, v253, 21
	s_nop 4
	global_load_dwordx4 v[58:61], v62, s[0:1]
	global_load_dwordx4 v[54:57], v62, s[0:1] offset:16
	v_readlane_b32 s0, v253, 22
	v_readlane_b32 s1, v253, 23
	s_nop 4
	global_load_dwordx4 v[66:69], v62, s[0:1]
	s_nop 0
	global_load_dwordx4 v[62:65], v62, s[0:1] offset:16
	s_waitcnt vmcnt(0)

;     __device__ __forceinline__ void operator()(const pg8::f32x4 (&acc)[2][2][4][2], const pg8::Unit& u, int wr, int wc, int fr, int fq) const {
;     ...
;                 const int row = row0 + ai * 128 + m * 16;
;                 const int tok = row & (SEQ - 1);
;                 bf16_t* rowp = base + (size_t)((row >> 13) * LP + PADF + NMETA + tok) * ldc + col0;
;                 const float scr = sc * rstd[row];
;                 f32x4 c0 = {1.f, 1.f, 1.f, 1.f}, c1 = c0, s0 = {0.f, 0.f, 0.f, 0.f}, s1 = s0;
;                 if (dorope) {
;                     const int pos = NMETA + tok;
;                     if (fq < 2) { c0 = *(const f32x4*)(ropec + pos * 8); c1 = *(const f32x4*)(ropec + pos * 8 + 4); s0 = *(const f32x4*)(ropes + pos * 8); s1 = *(const f32x4*)(ropes + pos * 8 + 4); }
;                 }
; #pragma unroll
;                 for (int bj = 0; bj < 2; ++bj) {
;                     f32x4 v0 = acc[ai][bj][m][0] * scr, v1 = acc[ai][bj][m][1] * scr;
.LBB0_391:
	v_mov_b32_e32 v71, v70
	v_cvt_pk_bf16_f32 v50, v50, v51
	v_cvt_pk_bf16_f32 v51, v52, v53
	v_cvt_pk_bf16_f32 v53, v48, v49
	v_mov_b32_e32 v48, v70
	v_mov_b32_e32 v49, v70
	s_mul_i32 s0, s2, 288
	s_mov_b32 s1, 0
	v_lshl_add_u64 v[46:47], v[232:233], 0, s[0:1]
	v_cvt_pk_bf16_f32 v52, v72, v73
	v_pk_mul_f32 v[44:45], v[44:45], v[48:49]
	v_pk_mul_f32 v[42:43], v[42:43], v[70:71]
	v_pk_mul_f32 v[40:41], v[40:41], v[48:49]
	s_and_b64 vcc, exec, s[46:47]
	v_pk_mul_f32 v[38:39], v[38:39], v[70:71]
	global_store_dwordx4 v[46:47], v[50:53], off
	s_cbranch_vccnz .LBB0_393
	v_and_b32_e32 v49, 64, v218
	v_xor_b32_e32 v48, 16, v218
	v_add_u32_e32 v49, 64, v49
	v_cmp_lt_i32_e32 vcc, v48, v49
	s_nop 1
	v_cndmask_b32_e32 v48, v218, v48, vcc
	v_lshlrev_b32_e32 v71, 2, v48
	ds_bpermute_b32 v48, v71, v42
	ds_bpermute_b32 v49, v71, v43
	ds_bpermute_b32 v50, v71, v38
	ds_bpermute_b32 v52, v71, v44
	ds_bpermute_b32 v53, v71, v45
	ds_bpermute_b32 v51, v71, v39
	ds_bpermute_b32 v70, v71, v40
	ds_bpermute_b32 v71, v71, v41
	s_waitcnt lgkmcnt(6)
	v_pk_mul_f32 v[48:49], v[66:67], v[48:49]
	s_waitcnt lgkmcnt(3)
	v_pk_mul_f32 v[52:53], v[68:69], v[52:53]
	v_pk_mul_f32 v[48:49], v[156:157], v[48:49]
	s_waitcnt lgkmcnt(2)
	v_pk_mul_f32 v[50:51], v[62:63], v[50:51]
	v_pk_fma_f32 v[42:43], v[42:43], v[58:59], v[48:49]
	s_waitcnt lgkmcnt(0)
	v_pk_mul_f32 v[48:49], v[64:65], v[70:71]
	v_pk_mul_f32 v[52:53], v[158:159], v[52:53]
	v_pk_mul_f32 v[50:51], v[156:157], v[50:51]
	v_pk_mul_f32 v[48:49], v[158:159], v[48:49]
	v_pk_fma_f32 v[44:45], v[44:45], v[60:61], v[52:53]
	v_pk_fma_f32 v[40:41], v[40:41], v[56:57], v[48:49]
	v_pk_fma_f32 v[38:39], v[38:39], v[54:55], v[50:51]

; __device__ __forceinline__ unsigned pk2(float lo, float hi) { f32x2v v = {lo, hi}; bf16x2_t b = __builtin_convertvector(v, bf16x2_t); return __builtin_bit_cast(unsigned, b); }
;     __device__ __forceinline__ void operator()(const pg8::f32x4 (&acc)[2][2][4][2], const pg8::Unit& u, int wr, int wc, int fr, int fq) const {
;     ...
;                 const int row = row0 + ai * 128 + m * 16;
;                 const int tok = row & (SEQ - 1);
;                 bf16_t* rowp = base + (size_t)((row >> 13) * LP + PADF + NMETA + tok) * ldc + col0;
;                 const float scr = sc * rstd[row];
;                 f32x4 c0 = {1.f, 1.f, 1.f, 1.f}, c1 = c0, s0 = {0.f, 0.f, 0.f, 0.f}, s1 = s0;
;                 if (dorope) {
;                     const int pos = NMETA + tok;
;                     if (fq < 2) { c0 = *(const f32x4*)(ropec + pos * 8); c1 = *(const f32x4*)(ropec + pos * 8 + 4); s0 = *(const f32x4*)(ropes + pos * 8); s1 = *(const f32x4*)(ropes + pos * 8 + 4); }
;     ...
;                     u32x4 w; w.x = pk2(v0[0], v0[1]); w.y = pk2(v0[2], v0[3]); w.z = pk2(v1[0], v1[1]); w.w = pk2(v1[2], v1[3]);
;                     *(u32x4*)(rowp + bj * 128) = w;
.LBB0_395:
	v_cvt_pk_bf16_f32 v42, v42, v43
	v_cvt_pk_bf16_f32 v43, v44, v45
	v_cvt_pk_bf16_f32 v44, v38, v39
	v_add_u32_e32 v38, 0xa0, v166
	v_cvt_pk_bf16_f32 v45, v40, v41
	global_store_dwordx4 v[46:47], v[42:45], off offset:256
	v_mov_b32_e32 v54, v229
	v_and_b32_e32 v58, 0x1fef, v38
	s_and_b64 vcc, exec, s[46:47]
	s_cbranch_vccnz .Lepi_nd7
	v_mov_b32_e32 v50, 0
	v_mov_b32_e32 v42, 1.0
	v_mov_b32_e32 v43, 1.0
	v_mov_b32_e32 v44, 1.0
	v_mov_b32_e32 v45, 1.0
	v_mov_b32_e32 v38, 1.0
	v_mov_b32_e32 v39, 1.0
	v_mov_b32_e32 v40, 1.0
	v_mov_b32_e32 v41, 1.0
	v_mov_b32_e32 v51, 0
	v_mov_b32_e32 v52, 0
	v_mov_b32_e32 v53, 0
	v_mov_b32_e32 v46, 0
	v_mov_b32_e32 v47, 0
	v_mov_b32_e32 v48, 0
	v_mov_b32_e32 v49, 0
.Lepi_nd7:
	s_and_saveexec_b64 s[20:21], s[30:31]
	s_cbranch_execz .LBB0_397
	v_readlane_b32 s0, v253, 20
	v_lshl_or_b32 v46, v58, 5, v220
	v_readlane_b32 s1, v253, 21
	s_nop 4
	global_load_dwordx4 v[42:45], v46, s[0:1]
	global_load_dwordx4 v[38:41], v46, s[0:1] offset:16
	v_readlane_b32 s0, v253, 22
	v_readlane_b32 s1, v253, 23
	s_nop 4
	global_load_dwordx4 v[50:53], v46, s[0:1]
	s_nop 0
	global_load_dwordx4 v[46:49], v46, s[0:1] offset:16
	s_waitcnt vmcnt(0)

; __device__ __forceinline__ unsigned pk2(float lo, float hi) { f32x2v v = {lo, hi}; bf16x2_t b = __builtin_convertvector(v, bf16x2_t); return __builtin_bit_cast(unsigned, b); }
;     __device__ __forceinline__ void operator()(const pg8::f32x4 (&acc)[2][2][4][2], const pg8::Unit& u, int wr, int wc, int fr, int fq) const {
;     ...
;                 bf16_t* rowp = base + (size_t)((row >> 13) * LP + PADF + NMETA + tok) * ldc + col0;
;                 const float scr = sc * rstd[row];
;                 f32x4 c0 = {1.f, 1.f, 1.f, 1.f}, c1 = c0, s0 = {0.f, 0.f, 0.f, 0.f}, s1 = s0;
;                 if (dorope) {
;                     const int pos = NMETA + tok;
;                     if (fq < 2) { c0 = *(const f32x4*)(ropec + pos * 8); c1 = *(const f32x4*)(ropec + pos * 8 + 4); s0 = *(const f32x4*)(ropes + pos * 8); s1 = *(const f32x4*)(ropes + pos * 8 + 4); }
;                 }
; #pragma unroll
;                 for (int bj = 0; bj < 2; ++bj) {
;                     f32x4 v0 = acc[ai][bj][m][0] * scr, v1 = acc[ai][bj][m][1] * scr;
;                     if (dorope) {
;                         f32x4 p0, p1;
; #pragma unroll
;                         for (int e = 0; e < 4; ++e) { p0[e] = __shfl_xor(v0[e], 16); p1[e] = __shfl_xor(v1[e], 16); }
;                         v0 = v0 * c0 + (p0 * s0) * sgn; v1 = v1 * c1 + (p1 * s1) * sgn;
;                     }
;                     if (silu) {
; #pragma unroll
;                         for (int e = 0; e < 4; ++e) { v0[e] = v0[e] * __builtin_amdgcn_rcpf(1.f + __builtin_amdgcn_exp2f(-LOG2E * v0[e])); v1[e] = v1[e] * __builtin_amdgcn_rcpf(1.f + __builtin_amdgcn_exp2f(-LOG2E * v1[e])); }
;                     }
;                     u32x4 w; w.x = pk2(v0[0], v0[1]); w.y = pk2(v0[2], v0[3]); w.z = pk2(v1[0], v1[1]); w.w = pk2(v1[2], v1[3]);
;                     *(u32x4*)(rowp + bj * 128) = w;
.LBB0_401:
	v_mov_b32_e32 v55, v54
	v_cvt_pk_bf16_f32 v34, v34, v35
	v_cvt_pk_bf16_f32 v35, v36, v37
	v_cvt_pk_bf16_f32 v37, v32, v33
	v_mov_b32_e32 v32, v54
	v_mov_b32_e32 v33, v54
	s_mul_i32 s0, s2, 320
	s_mov_b32 s1, 0
	v_lshl_add_u64 v[30:31], v[232:233], 0, s[0:1]
	v_cvt_pk_bf16_f32 v36, v56, v57
	v_pk_mul_f32 v[28:29], v[28:29], v[32:33]
	v_pk_mul_f32 v[26:27], v[26:27], v[54:55]
	v_pk_mul_f32 v[24:25], v[24:25], v[32:33]
	s_and_b64 vcc, exec, s[46:47]
	v_pk_mul_f32 v[22:23], v[22:23], v[54:55]
	global_store_dwordx4 v[30:31], v[34:37], off
	s_cbranch_vccnz .LBB0_403
	v_and_b32_e32 v33, 64, v218
	v_xor_b32_e32 v32, 16, v218
	v_add_u32_e32 v33, 64, v33
	v_cmp_lt_i32_e32 vcc, v32, v33
	s_nop 1
	v_cndmask_b32_e32 v32, v218, v32, vcc
	v_lshlrev_b32_e32 v55, 2, v32
	ds_bpermute_b32 v32, v55, v26
	ds_bpermute_b32 v33, v55, v27
	ds_bpermute_b32 v34, v55, v22
	ds_bpermute_b32 v36, v55, v28
	ds_bpermute_b32 v37, v55, v29
	ds_bpermute_b32 v35, v55, v23
	ds_bpermute_b32 v54, v55, v24
	ds_bpermute_b32 v55, v55, v25
	s_waitcnt lgkmcnt(6)
	v_pk_mul_f32 v[32:33], v[50:51], v[32:33]
	s_waitcnt lgkmcnt(3)
	v_pk_mul_f32 v[36:37], v[52:53], v[36:37]
	v_pk_mul_f32 v[32:33], v[156:157], v[32:33]
	s_waitcnt lgkmcnt(2)
	v_pk_mul_f32 v[34:35], v[46:47], v[34:35]
	v_pk_fma_f32 v[26:27], v[26:27], v[42:43], v[32:33]
	s_waitcnt lgkmcnt(0)
	v_pk_mul_f32 v[32:33], v[48:49], v[54:55]
	v_pk_mul_f32 v[36:37], v[158:159], v[36:37]
	v_pk_mul_f32 v[34:35], v[156:157], v[34:35]
	v_pk_mul_f32 v[32:33], v[158:159], v[32:33]
	v_pk_fma_f32 v[28:29], v[28:29], v[44:45], v[36:37]
	v_pk_fma_f32 v[24:25], v[24:25], v[40:41], v[32:33]
	v_pk_fma_f32 v[22:23], v[22:23], v[38:39], v[34:35]

; __device__ __forceinline__ unsigned pk2(float lo, float hi) { f32x2v v = {lo, hi}; bf16x2_t b = __builtin_convertvector(v, bf16x2_t); return __builtin_bit_cast(unsigned, b); }
;     __device__ __forceinline__ void operator()(const pg8::f32x4 (&acc)[2][2][4][2], const pg8::Unit& u, int wr, int wc, int fr, int fq) const {
;     ...
;                 const int row = row0 + ai * 128 + m * 16;
;                 const int tok = row & (SEQ - 1);
;                 bf16_t* rowp = base + (size_t)((row >> 13) * LP + PADF + NMETA + tok) * ldc + col0;
;                 const float scr = sc * rstd[row];
;                 f32x4 c0 = {1.f, 1.f, 1.f, 1.f}, c1 = c0, s0 = {0.f, 0.f, 0.f, 0.f}, s1 = s0;
;                 if (dorope) {
;                     const int pos = NMETA + tok;
;                     if (fq < 2) { c0 = *(const f32x4*)(ropec + pos * 8); c1 = *(const f32x4*)(ropec + pos * 8 + 4); s0 = *(const f32x4*)(ropes + pos * 8); s1 = *(const f32x4*)(ropes + pos * 8 + 4); }
;     ...
;                     u32x4 w; w.x = pk2(v0[0], v0[1]); w.y = pk2(v0[2], v0[3]); w.z = pk2(v1[0], v1[1]); w.w = pk2(v1[2], v1[3]);
;                     *(u32x4*)(rowp + bj * 128) = w;
.LBB0_405:
	v_cvt_pk_bf16_f32 v26, v26, v27
	v_cvt_pk_bf16_f32 v27, v28, v29
	v_cvt_pk_bf16_f32 v28, v22, v23
	v_add_u32_e32 v22, 0xb0, v166
	v_cvt_pk_bf16_f32 v29, v24, v25
	global_store_dwordx4 v[30:31], v[26:29], off offset:256
	v_mov_b32_e32 v38, v230
	v_and_b32_e32 v42, 0x1fff, v22
	s_and_b64 vcc, exec, s[46:47]
	s_cbranch_vccnz .Lepi_nd8
	v_mov_b32_e32 v34, 0
	v_mov_b32_e32 v26, 1.0
	v_mov_b32_e32 v27, 1.0
	v_mov_b32_e32 v28, 1.0
	v_mov_b32_e32 v29, 1.0
	v_mov_b32_e32 v22, 1.0
	v_mov_b32_e32 v23, 1.0
	v_mov_b32_e32 v24, 1.0
	v_mov_b32_e32 v25, 1.0
	v_mov_b32_e32 v35, 0
	v_mov_b32_e32 v36, 0
	v_mov_b32_e32 v37, 0
	v_mov_b32_e32 v30, 0
	v_mov_b32_e32 v31, 0
	v_mov_b32_e32 v32, 0
	v_mov_b32_e32 v33, 0
.Lepi_nd8:
	s_and_saveexec_b64 s[20:21], s[30:31]
	s_cbranch_execz .LBB0_407
	v_readlane_b32 s0, v253, 20
	v_lshl_add_u32 v30, v42, 5, v220
	v_readlane_b32 s1, v253, 21
	s_nop 4
	global_load_dwordx4 v[26:29], v30, s[0:1]
	global_load_dwordx4 v[22:25], v30, s[0:1] offset:16
	v_readlane_b32 s0, v253, 22
	v_readlane_b32 s1, v253, 23
	s_nop 4
	global_load_dwordx4 v[34:37], v30, s[0:1]
	s_nop 0
	global_load_dwordx4 v[30:33], v30, s[0:1] offset:16
	s_waitcnt vmcnt(0)

; __device__ __forceinline__ unsigned pk2(float lo, float hi) { f32x2v v = {lo, hi}; bf16x2_t b = __builtin_convertvector(v, bf16x2_t); return __builtin_bit_cast(unsigned, b); }
;     __device__ __forceinline__ void operator()(const pg8::f32x4 (&acc)[2][2][4][2], const pg8::Unit& u, int wr, int wc, int fr, int fq) const {
;     ...
;                 bf16_t* rowp = base + (size_t)((row >> 13) * LP + PADF + NMETA + tok) * ldc + col0;
;                 const float scr = sc * rstd[row];
;                 f32x4 c0 = {1.f, 1.f, 1.f, 1.f}, c1 = c0, s0 = {0.f, 0.f, 0.f, 0.f}, s1 = s0;
;                 if (dorope) {
;                     const int pos = NMETA + tok;
;                     if (fq < 2) { c0 = *(const f32x4*)(ropec + pos * 8); c1 = *(const f32x4*)(ropec + pos * 8 + 4); s0 = *(const f32x4*)(ropes + pos * 8); s1 = *(const f32x4*)(ropes + pos * 8 + 4); }
;                 }
; #pragma unroll
;                 for (int bj = 0; bj < 2; ++bj) {
;                     f32x4 v0 = acc[ai][bj][m][0] * scr, v1 = acc[ai][bj][m][1] * scr;
;                     if (dorope) {
;                         f32x4 p0, p1;
; #pragma unroll
;                         for (int e = 0; e < 4; ++e) { p0[e] = __shfl_xor(v0[e], 16); p1[e] = __shfl_xor(v1[e], 16); }
;                         v0 = v0 * c0 + (p0 * s0) * sgn; v1 = v1 * c1 + (p1 * s1) * sgn;
;                     }
;                     if (silu) {
; #pragma unroll
;                         for (int e = 0; e < 4; ++e) { v0[e] = v0[e] * __builtin_amdgcn_rcpf(1.f + __builtin_amdgcn_exp2f(-LOG2E * v0[e])); v1[e] = v1[e] * __builtin_amdgcn_rcpf(1.f + __builtin_amdgcn_exp2f(-LOG2E * v1[e])); }
;                     }
;                     u32x4 w; w.x = pk2(v0[0], v0[1]); w.y = pk2(v0[2], v0[3]); w.z = pk2(v1[0], v1[1]); w.w = pk2(v1[2], v1[3]);
;                     *(u32x4*)(rowp + bj * 128) = w;
.LBB0_411:
	v_mov_b32_e32 v39, v38
	v_cvt_pk_bf16_f32 v18, v18, v19
	v_cvt_pk_bf16_f32 v19, v20, v21
	v_cvt_pk_bf16_f32 v21, v12, v13
	v_mov_b32_e32 v12, v38
	v_mov_b32_e32 v13, v38
	s_mul_i32 s0, s2, 352
	s_mov_b32 s1, 0
	v_lshl_add_u64 v[10:11], v[232:233], 0, s[0:1]
	v_cvt_pk_bf16_f32 v20, v40, v41
	v_pk_mul_f32 v[8:9], v[8:9], v[12:13]
	v_pk_mul_f32 v[6:7], v[6:7], v[38:39]
	v_pk_mul_f32 v[4:5], v[4:5], v[12:13]
	s_and_b64 vcc, exec, s[46:47]
	v_pk_mul_f32 v[2:3], v[2:3], v[38:39]
	global_store_dwordx4 v[10:11], v[18:21], off
	s_cbranch_vccnz .LBB0_413
	v_and_b32_e32 v13, 64, v218
	v_xor_b32_e32 v12, 16, v218
	v_add_u32_e32 v13, 64, v13
	v_cmp_lt_i32_e32 vcc, v12, v13
	s_nop 1
	v_cndmask_b32_e32 v12, v218, v12, vcc
	v_lshlrev_b32_e32 v39, 2, v12
	ds_bpermute_b32 v12, v39, v6
	ds_bpermute_b32 v13, v39, v7
	ds_bpermute_b32 v18, v39, v2
	ds_bpermute_b32 v20, v39, v8
	ds_bpermute_b32 v21, v39, v9
	ds_bpermute_b32 v19, v39, v3
	ds_bpermute_b32 v38, v39, v4
	ds_bpermute_b32 v39, v39, v5
	s_waitcnt lgkmcnt(6)
	v_pk_mul_f32 v[12:13], v[34:35], v[12:13]
	s_waitcnt lgkmcnt(3)
	v_pk_mul_f32 v[20:21], v[36:37], v[20:21]
	v_pk_mul_f32 v[12:13], v[156:157], v[12:13]
	s_waitcnt lgkmcnt(2)
	v_pk_mul_f32 v[18:19], v[30:31], v[18:19]
	v_pk_fma_f32 v[6:7], v[6:7], v[26:27], v[12:13]
	s_waitcnt lgkmcnt(0)
	v_pk_mul_f32 v[12:13], v[32:33], v[38:39]
	v_pk_mul_f32 v[20:21], v[158:159], v[20:21]
	v_pk_mul_f32 v[18:19], v[156:157], v[18:19]
	v_pk_mul_f32 v[12:13], v[158:159], v[12:13]
	v_pk_fma_f32 v[8:9], v[8:9], v[28:29], v[20:21]
	v_pk_fma_f32 v[4:5], v[4:5], v[24:25], v[12:13]
	v_pk_fma_f32 v[2:3], v[2:3], v[22:23], v[18:19]
